# in-proj local-attention q/k tiles (wide map): the two interleaved 16-byte stores per row re-paired with permlane16/32 swaps into 64-byte contiguous pieces; on top of v23
# baseline (speedup 1.0000x reference)
; __device__ __forceinline__ float sigm(float x) { return __builtin_amdgcn_rcpf(1.0f + __expf(-x)); }
; __device__ __forceinline__ u32x4 pack8(f32x4 a, f32x4 b) { u32x4 w; w.x = cvt_pk_bf16(a[0], a[1]); w.y = cvt_pk_bf16(a[2], a[3]); w.z = cvt_pk_bf16(b[0], b[1]); w.w = cvt_pk_bf16(b[2], b[3]); return w; }
;     __device__ __forceinline__ void operator()(const f32x4 (&acc)[2][2][4][2], const Unit& u, int wr, int wc, int fr_, int fq_) const {
;     ...
;             bf16_t* base; int pitch; float sc = 1.0f; bool gate = false;
;             if (pn < 5) { base = QB + 256 * (pn - 3); pitch = 512; sc = C2; }
;             else { base = KB + 256 * (pn - 5); pitch = 512; }
; #pragma unroll
;             for (int ai = 0; ai < 2; ++ai)
; #pragma unroll
;                 for (int m = 0; m < 4; ++m) {
;                     const int row = u.pm * 256 + ai * 128 + wr * 64 + m * 16 + fr;
;                     const float rs = rs8[ai][m] * sc;
;                     bf16_t* dst = base + (size_t)row * pitch + 64 * wc + 16 * fq;
; #pragma unroll
;                     for (int bj = 0; bj < 2; ++bj) {
;                         f32x4 a = acc[ai][bj][m][0] * rs, b = acc[ai][bj][m][1] * rs;
;                         if (gate) {
; #pragma unroll
;                             for (int i = 0; i < 4; ++i) { a[i] = sigm(a[i]); b[i] = sigm(b[i]); }
;                         }
;                         *(u32x4*)(dst + 8 * bj) = pack8(a, b);
;                     }
;                 }
.LBB0_413:
	s_add_i32 s0, s40, -7
	s_cmp_gt_u32 s0, 1
	s_mov_b64 s[0:1], -1
	s_cbranch_scc0 .LBB0_419
	s_cmp_lt_u32 s40, 9
	v_lshlrev_b64 v[160:161], 10, v[186:187]
	v_lshlrev_b64 v[158:159], 10, v[184:185]
	v_lshlrev_b64 v[156:157], 10, v[182:183]
	v_lshlrev_b64 v[152:153], 10, v[180:181]
	v_lshlrev_b64 v[144:145], 10, v[178:179]
	v_lshlrev_b64 v[140:141], 10, v[176:177]
	v_lshlrev_b64 v[136:137], 10, v[174:175]
	v_lshlrev_b64 v[134:135], 10, v[172:173]
	s_cbranch_scc0 .LBB0_416
	v_lshlrev_b32_e32 v244, 4, v188
	v_sub_u32_e32 v244, 0, v244
	v_ashrrev_i32_e32 v245, 31, v244
	s_cmp_lt_u32 s40, 5
	s_cselect_b64 vcc, -1, 0
	s_and_b64 s[0:1], vcc, exec
	v_readlane_b32 s30, v253, 15
	v_readlane_b32 s36, v253, 17
	s_movk_i32 s0, 0xfa00
	v_readlane_b32 s31, v253, 16
	v_readlane_b32 s37, v253, 18
	s_cselect_b32 s0, s0, 0xfffff600
	s_cselect_b32 s1, s31, s37
	s_cselect_b32 s21, s30, s36
	s_lshl_b32 s23, s40, 9
	s_add_u32 s21, s21, s23
	s_addc_u32 s1, s1, 0
	s_add_u32 s0, s21, s0
	v_readlane_b32 s21, v255, 39
	v_mov_b32_e32 v131, 0x3e38aa3b
	s_addc_u32 s1, s1, -1
	s_lshl_b32 s21, s21, 1
	v_cndmask_b32_e32 v131, 1.0, v131, vcc
	s_add_u32 s0, s0, s21
	v_lshlrev_b32_e32 v150, 4, v188
	s_addc_u32 s1, s1, 0
	v_ashrrev_i32_e32 v151, 31, v150
	v_mul_f32_e32 v196, v131, v0
	v_lshl_add_u64 v[150:151], v[150:151], 1, s[0:1]
	v_pk_mul_f32 v[194:195], v[114:115], v[196:197] op_sel_hi:[1,0]
	v_pk_mul_f32 v[192:193], v[118:119], v[196:197] op_sel_hi:[1,0]
	v_lshl_add_u64 v[208:209], v[150:151], 0, v[160:161]
	v_pk_mul_f32 v[212:213], v[116:117], v[196:197] op_sel_hi:[1,0]
	v_pk_mul_f32 v[214:215], v[120:121], v[196:197] op_sel_hi:[1,0]
	v_cvt_pk_bf16_f32 v192, v192, v193
	s_mov_b64 s[0:1], 0
	v_cvt_pk_bf16_f32 v193, v214, v215
	v_cvt_pk_bf16_f32 v194, v194, v195
	v_cvt_pk_bf16_f32 v195, v212, v213
	v_mov_b32_e32 v234, v192
	v_mov_b32_e32 v235, v193
	v_mov_b32_e32 v236, v194
	v_mov_b32_e32 v237, v195
	v_pk_mul_f32 v[212:213], v[124:125], v[196:197] op_sel_hi:[1,0]
	v_pk_mul_f32 v[214:215], v[128:129], v[196:197] op_sel_hi:[1,0]
	v_pk_mul_f32 v[194:195], v[122:123], v[196:197] op_sel_hi:[1,0]
	v_pk_mul_f32 v[192:193], v[126:127], v[196:197] op_sel_hi:[1,0]
	v_mul_f32_e32 v196, v131, v154
	v_cvt_pk_bf16_f32 v192, v192, v193
	v_cvt_pk_bf16_f32 v193, v214, v215
	v_cvt_pk_bf16_f32 v194, v194, v195
	v_cvt_pk_bf16_f32 v195, v212, v213
	v_mov_b32_e32 v238, v192
	v_mov_b32_e32 v239, v193
	v_mov_b32_e32 v240, v194
	v_mov_b32_e32 v241, v195
	s_nop 1
	v_permlane16_swap_b32_e32 v234, v238
	v_permlane16_swap_b32_e32 v235, v239
	v_permlane16_swap_b32_e32 v236, v240
	v_permlane16_swap_b32_e32 v237, v241
	v_permlane32_swap_b32_e32 v234, v238
	v_permlane32_swap_b32_e32 v235, v239
	v_permlane32_swap_b32_e32 v236, v240
	v_permlane32_swap_b32_e32 v237, v241
	v_lshl_add_u64 v[242:243], v[208:209], 0, v[244:245]
	global_store_dwordx4 v[242:243], v[234:237], off
	global_store_dwordx4 v[242:243], v[238:241], off offset:64
	v_lshl_add_u64 v[208:209], v[150:151], 0, v[158:159]
	v_pk_mul_f32 v[212:213], v[100:101], v[196:197] op_sel_hi:[1,0]
	v_pk_mul_f32 v[194:195], v[98:99], v[196:197] op_sel_hi:[1,0]
	v_pk_mul_f32 v[192:193], v[106:107], v[196:197] op_sel_hi:[1,0]
	v_pk_mul_f32 v[214:215], v[108:109], v[196:197] op_sel_hi:[1,0]
	v_cvt_pk_bf16_f32 v192, v192, v193
	s_nop 0
	v_cvt_pk_bf16_f32 v193, v214, v215
	v_cvt_pk_bf16_f32 v194, v194, v195
	v_cvt_pk_bf16_f32 v195, v212, v213
	v_mov_b32_e32 v234, v192
	v_mov_b32_e32 v235, v193
	v_mov_b32_e32 v236, v194
	v_mov_b32_e32 v237, v195
	v_pk_mul_f32 v[212:213], v[104:105], v[196:197] op_sel_hi:[1,0]
	v_pk_mul_f32 v[214:215], v[112:113], v[196:197] op_sel_hi:[1,0]
	v_pk_mul_f32 v[194:195], v[102:103], v[196:197] op_sel_hi:[1,0]
	v_pk_mul_f32 v[192:193], v[110:111], v[196:197] op_sel_hi:[1,0]
	v_mul_f32_e32 v196, v131, v148
	v_cvt_pk_bf16_f32 v192, v192, v193
	v_cvt_pk_bf16_f32 v193, v214, v215
	v_cvt_pk_bf16_f32 v194, v194, v195
	v_cvt_pk_bf16_f32 v195, v212, v213
	v_mov_b32_e32 v238, v192
	v_mov_b32_e32 v239, v193
	v_mov_b32_e32 v240, v194
	v_mov_b32_e32 v241, v195
	s_nop 1
	v_permlane16_swap_b32_e32 v234, v238
	v_permlane16_swap_b32_e32 v235, v239
	v_permlane16_swap_b32_e32 v236, v240
	v_permlane16_swap_b32_e32 v237, v241
	v_permlane32_swap_b32_e32 v234, v238
	v_permlane32_swap_b32_e32 v235, v239
	v_permlane32_swap_b32_e32 v236, v240
	v_permlane32_swap_b32_e32 v237, v241
	v_lshl_add_u64 v[242:243], v[208:209], 0, v[244:245]
	global_store_dwordx4 v[242:243], v[234:237], off
	global_store_dwordx4 v[242:243], v[238:241], off offset:64
	v_lshl_add_u64 v[208:209], v[150:151], 0, v[156:157]
	v_pk_mul_f32 v[212:213], v[84:85], v[196:197] op_sel_hi:[1,0]
	v_pk_mul_f32 v[194:195], v[82:83], v[196:197] op_sel_hi:[1,0]
	v_pk_mul_f32 v[192:193], v[90:91], v[196:197] op_sel_hi:[1,0]
	v_pk_mul_f32 v[214:215], v[92:93], v[196:197] op_sel_hi:[1,0]
	v_cvt_pk_bf16_f32 v192, v192, v193
	s_nop 0
	v_cvt_pk_bf16_f32 v193, v214, v215
	v_cvt_pk_bf16_f32 v194, v194, v195
	v_cvt_pk_bf16_f32 v195, v212, v213
	v_mov_b32_e32 v234, v192
	v_mov_b32_e32 v235, v193
	v_mov_b32_e32 v236, v194
	v_mov_b32_e32 v237, v195
	v_pk_mul_f32 v[212:213], v[88:89], v[196:197] op_sel_hi:[1,0]
	v_pk_mul_f32 v[214:215], v[96:97], v[196:197] op_sel_hi:[1,0]
	v_pk_mul_f32 v[194:195], v[86:87], v[196:197] op_sel_hi:[1,0]
	v_pk_mul_f32 v[192:193], v[94:95], v[196:197] op_sel_hi:[1,0]
	v_mul_f32_e32 v196, v131, v146
	v_cvt_pk_bf16_f32 v192, v192, v193
	v_cvt_pk_bf16_f32 v193, v214, v215
	v_cvt_pk_bf16_f32 v194, v194, v195
	v_cvt_pk_bf16_f32 v195, v212, v213
	v_mov_b32_e32 v238, v192
	v_mov_b32_e32 v239, v193
	v_mov_b32_e32 v240, v194
	v_mov_b32_e32 v241, v195
	s_nop 1
	v_permlane16_swap_b32_e32 v234, v238
; __device__ __forceinline__ float sigm(float x) { return __builtin_amdgcn_rcpf(1.0f + __expf(-x)); }
; __device__ __forceinline__ u32x4 pack8(f32x4 a, f32x4 b) { u32x4 w; w.x = cvt_pk_bf16(a[0], a[1]); w.y = cvt_pk_bf16(a[2], a[3]); w.z = cvt_pk_bf16(b[0], b[1]); w.w = cvt_pk_bf16(b[2], b[3]); return w; }
;     __device__ __forceinline__ void operator()(const f32x4 (&acc)[2][2][4][2], const Unit& u, int wr, int wc, int fr_, int fq_) const {
;     ...
;                 for (int m = 0; m < 4; ++m) {
;                     const int row = u.pm * 256 + ai * 128 + wr * 64 + m * 16 + fr;
;                     const float rs = rs8[ai][m] * sc;
;                     bf16_t* dst = base + (size_t)row * pitch + 64 * wc + 16 * fq;
; #pragma unroll
;                     for (int bj = 0; bj < 2; ++bj) {
;                         f32x4 a = acc[ai][bj][m][0] * rs, b = acc[ai][bj][m][1] * rs;
;                         if (gate) {
; #pragma unroll
;                             for (int i = 0; i < 4; ++i) { a[i] = sigm(a[i]); b[i] = sigm(b[i]); }
;                         }
;                         *(u32x4*)(dst + 8 * bj) = pack8(a, b);
;                     }
	v_permlane16_swap_b32_e32 v235, v239
	v_permlane16_swap_b32_e32 v236, v240
	v_permlane16_swap_b32_e32 v237, v241
	v_permlane32_swap_b32_e32 v234, v238
	v_permlane32_swap_b32_e32 v235, v239
	v_permlane32_swap_b32_e32 v236, v240
	v_permlane32_swap_b32_e32 v237, v241
	v_lshl_add_u64 v[242:243], v[208:209], 0, v[244:245]
	global_store_dwordx4 v[242:243], v[234:237], off
	global_store_dwordx4 v[242:243], v[238:241], off offset:64
	v_lshl_add_u64 v[208:209], v[150:151], 0, v[152:153]
	v_pk_mul_f32 v[212:213], v[68:69], v[196:197] op_sel_hi:[1,0]
	v_pk_mul_f32 v[194:195], v[66:67], v[196:197] op_sel_hi:[1,0]
	v_pk_mul_f32 v[192:193], v[74:75], v[196:197] op_sel_hi:[1,0]
	v_pk_mul_f32 v[214:215], v[76:77], v[196:197] op_sel_hi:[1,0]
	v_cvt_pk_bf16_f32 v192, v192, v193
	s_nop 0
	v_cvt_pk_bf16_f32 v193, v214, v215
	v_cvt_pk_bf16_f32 v194, v194, v195
	v_cvt_pk_bf16_f32 v195, v212, v213
	v_mov_b32_e32 v234, v192
	v_mov_b32_e32 v235, v193
	v_mov_b32_e32 v236, v194
	v_mov_b32_e32 v237, v195
	v_pk_mul_f32 v[212:213], v[72:73], v[196:197] op_sel_hi:[1,0]
	v_pk_mul_f32 v[214:215], v[80:81], v[196:197] op_sel_hi:[1,0]
	v_pk_mul_f32 v[194:195], v[70:71], v[196:197] op_sel_hi:[1,0]
	v_pk_mul_f32 v[192:193], v[78:79], v[196:197] op_sel_hi:[1,0]
	v_mul_f32_e32 v196, v131, v142
	v_cvt_pk_bf16_f32 v192, v192, v193
	v_cvt_pk_bf16_f32 v193, v214, v215
	v_cvt_pk_bf16_f32 v194, v194, v195
	v_cvt_pk_bf16_f32 v195, v212, v213
	v_mov_b32_e32 v238, v192
	v_mov_b32_e32 v239, v193
	v_mov_b32_e32 v240, v194
	v_mov_b32_e32 v241, v195
	s_nop 1
	v_permlane16_swap_b32_e32 v234, v238
	v_permlane16_swap_b32_e32 v235, v239
	v_permlane16_swap_b32_e32 v236, v240
	v_permlane16_swap_b32_e32 v237, v241
	v_permlane32_swap_b32_e32 v234, v238
	v_permlane32_swap_b32_e32 v235, v239
	v_permlane32_swap_b32_e32 v236, v240
	v_permlane32_swap_b32_e32 v237, v241
	v_lshl_add_u64 v[242:243], v[208:209], 0, v[244:245]
	global_store_dwordx4 v[242:243], v[234:237], off
	global_store_dwordx4 v[242:243], v[238:241], off offset:64
	v_lshl_add_u64 v[208:209], v[150:151], 0, v[144:145]
	v_pk_mul_f32 v[212:213], v[52:53], v[196:197] op_sel_hi:[1,0]
	v_pk_mul_f32 v[194:195], v[50:51], v[196:197] op_sel_hi:[1,0]
	v_pk_mul_f32 v[192:193], v[58:59], v[196:197] op_sel_hi:[1,0]
	v_pk_mul_f32 v[214:215], v[60:61], v[196:197] op_sel_hi:[1,0]
	v_cvt_pk_bf16_f32 v192, v192, v193
	s_nop 0
	v_cvt_pk_bf16_f32 v193, v214, v215
	v_cvt_pk_bf16_f32 v194, v194, v195
	v_cvt_pk_bf16_f32 v195, v212, v213
	v_mov_b32_e32 v234, v192
	v_mov_b32_e32 v235, v193
	v_mov_b32_e32 v236, v194
	v_mov_b32_e32 v237, v195
	v_pk_mul_f32 v[212:213], v[56:57], v[196:197] op_sel_hi:[1,0]
	v_pk_mul_f32 v[214:215], v[64:65], v[196:197] op_sel_hi:[1,0]
	v_pk_mul_f32 v[194:195], v[54:55], v[196:197] op_sel_hi:[1,0]
	v_pk_mul_f32 v[192:193], v[62:63], v[196:197] op_sel_hi:[1,0]
	v_mul_f32_e32 v196, v131, v138
	v_cvt_pk_bf16_f32 v192, v192, v193
	v_cvt_pk_bf16_f32 v193, v214, v215
	v_cvt_pk_bf16_f32 v194, v194, v195
	v_cvt_pk_bf16_f32 v195, v212, v213
	v_mov_b32_e32 v238, v192
	v_mov_b32_e32 v239, v193
	v_mov_b32_e32 v240, v194
	v_mov_b32_e32 v241, v195
	s_nop 1
	v_permlane16_swap_b32_e32 v234, v238
	v_permlane16_swap_b32_e32 v235, v239
	v_permlane16_swap_b32_e32 v236, v240
	v_permlane16_swap_b32_e32 v237, v241
	v_permlane32_swap_b32_e32 v234, v238
	v_permlane32_swap_b32_e32 v235, v239
	v_permlane32_swap_b32_e32 v236, v240
	v_permlane32_swap_b32_e32 v237, v241
	v_lshl_add_u64 v[242:243], v[208:209], 0, v[244:245]
	global_store_dwordx4 v[242:243], v[234:237], off
	global_store_dwordx4 v[242:243], v[238:241], off offset:64
	v_lshl_add_u64 v[208:209], v[150:151], 0, v[140:141]
	v_pk_mul_f32 v[212:213], v[36:37], v[196:197] op_sel_hi:[1,0]
	v_pk_mul_f32 v[194:195], v[34:35], v[196:197] op_sel_hi:[1,0]
	v_pk_mul_f32 v[192:193], v[42:43], v[196:197] op_sel_hi:[1,0]
	v_pk_mul_f32 v[214:215], v[44:45], v[196:197] op_sel_hi:[1,0]
	v_cvt_pk_bf16_f32 v192, v192, v193
	s_nop 0
	v_cvt_pk_bf16_f32 v193, v214, v215
	v_cvt_pk_bf16_f32 v194, v194, v195
	v_cvt_pk_bf16_f32 v195, v212, v213
	v_mov_b32_e32 v234, v192
	v_mov_b32_e32 v235, v193
	v_mov_b32_e32 v236, v194
	v_mov_b32_e32 v237, v195
; __device__ __forceinline__ float sigm(float x) { return __builtin_amdgcn_rcpf(1.0f + __expf(-x)); }
; __device__ __forceinline__ u32x4 pack8(f32x4 a, f32x4 b) { u32x4 w; w.x = cvt_pk_bf16(a[0], a[1]); w.y = cvt_pk_bf16(a[2], a[3]); w.z = cvt_pk_bf16(b[0], b[1]); w.w = cvt_pk_bf16(b[2], b[3]); return w; }
;     __device__ __forceinline__ void operator()(const f32x4 (&acc)[2][2][4][2], const Unit& u, int wr, int wc, int fr_, int fq_) const {
;     ...
;                 for (int m = 0; m < 4; ++m) {
;                     const int row = u.pm * 256 + ai * 128 + wr * 64 + m * 16 + fr;
;                     const float rs = rs8[ai][m] * sc;
;                     bf16_t* dst = base + (size_t)row * pitch + 64 * wc + 16 * fq;
; #pragma unroll
;                     for (int bj = 0; bj < 2; ++bj) {
;                         f32x4 a = acc[ai][bj][m][0] * rs, b = acc[ai][bj][m][1] * rs;
;                         if (gate) {
; #pragma unroll
;                             for (int i = 0; i < 4; ++i) { a[i] = sigm(a[i]); b[i] = sigm(b[i]); }
;                         }
;                         *(u32x4*)(dst + 8 * bj) = pack8(a, b);
;                     }
	v_pk_mul_f32 v[212:213], v[40:41], v[196:197] op_sel_hi:[1,0]
	v_pk_mul_f32 v[214:215], v[48:49], v[196:197] op_sel_hi:[1,0]
	v_pk_mul_f32 v[194:195], v[38:39], v[196:197] op_sel_hi:[1,0]
	v_pk_mul_f32 v[192:193], v[46:47], v[196:197] op_sel_hi:[1,0]
	v_mul_f32_e32 v196, v131, v132
	v_cvt_pk_bf16_f32 v192, v192, v193
	v_cvt_pk_bf16_f32 v193, v214, v215
	v_cvt_pk_bf16_f32 v194, v194, v195
	v_cvt_pk_bf16_f32 v195, v212, v213
	v_mov_b32_e32 v238, v192
	v_mov_b32_e32 v239, v193
	v_mov_b32_e32 v240, v194
	v_mov_b32_e32 v241, v195
	s_nop 1
	v_permlane16_swap_b32_e32 v234, v238
	v_permlane16_swap_b32_e32 v235, v239
	v_permlane16_swap_b32_e32 v236, v240
	v_permlane16_swap_b32_e32 v237, v241
	v_permlane32_swap_b32_e32 v234, v238
	v_permlane32_swap_b32_e32 v235, v239
	v_permlane32_swap_b32_e32 v236, v240
	v_permlane32_swap_b32_e32 v237, v241
	v_lshl_add_u64 v[242:243], v[208:209], 0, v[244:245]
	global_store_dwordx4 v[242:243], v[234:237], off
	global_store_dwordx4 v[242:243], v[238:241], off offset:64
	v_lshl_add_u64 v[208:209], v[150:151], 0, v[136:137]
	v_pk_mul_f32 v[212:213], v[20:21], v[196:197] op_sel_hi:[1,0]
	v_pk_mul_f32 v[194:195], v[18:19], v[196:197] op_sel_hi:[1,0]
	v_pk_mul_f32 v[192:193], v[26:27], v[196:197] op_sel_hi:[1,0]
	v_pk_mul_f32 v[214:215], v[28:29], v[196:197] op_sel_hi:[1,0]
	v_cvt_pk_bf16_f32 v192, v192, v193
	v_lshl_add_u64 v[150:151], v[150:151], 0, v[134:135]
	v_cvt_pk_bf16_f32 v193, v214, v215
	v_cvt_pk_bf16_f32 v194, v194, v195
	v_cvt_pk_bf16_f32 v195, v212, v213
	v_mov_b32_e32 v234, v192
	v_mov_b32_e32 v235, v193
	v_mov_b32_e32 v236, v194
	v_mov_b32_e32 v237, v195
	v_pk_mul_f32 v[212:213], v[24:25], v[196:197] op_sel_hi:[1,0]
	v_pk_mul_f32 v[214:215], v[32:33], v[196:197] op_sel_hi:[1,0]
	v_pk_mul_f32 v[194:195], v[22:23], v[196:197] op_sel_hi:[1,0]
	v_pk_mul_f32 v[192:193], v[30:31], v[196:197] op_sel_hi:[1,0]
	v_mul_f32_e32 v196, v131, v130
	v_cvt_pk_bf16_f32 v192, v192, v193
	v_cvt_pk_bf16_f32 v193, v214, v215
	v_cvt_pk_bf16_f32 v194, v194, v195
	v_cvt_pk_bf16_f32 v195, v212, v213
	v_mov_b32_e32 v238, v192
	v_mov_b32_e32 v239, v193
	v_mov_b32_e32 v240, v194
	v_mov_b32_e32 v241, v195
	s_nop 1
	v_permlane16_swap_b32_e32 v234, v238
	v_permlane16_swap_b32_e32 v235, v239
	v_permlane16_swap_b32_e32 v236, v240
	v_permlane16_swap_b32_e32 v237, v241
	v_permlane32_swap_b32_e32 v234, v238
	v_permlane32_swap_b32_e32 v235, v239
	v_permlane32_swap_b32_e32 v236, v240
	v_permlane32_swap_b32_e32 v237, v241
	v_lshl_add_u64 v[242:243], v[208:209], 0, v[244:245]
	global_store_dwordx4 v[242:243], v[234:237], off
	global_store_dwordx4 v[242:243], v[238:241], off offset:64
	v_pk_mul_f32 v[208:209], v[4:5], v[196:197] op_sel_hi:[1,0]
	v_pk_mul_f32 v[212:213], v[12:13], v[196:197] op_sel_hi:[1,0]
	v_pk_mul_f32 v[194:195], v[2:3], v[196:197] op_sel_hi:[1,0]
	v_pk_mul_f32 v[192:193], v[10:11], v[196:197] op_sel_hi:[1,0]
	s_nop 0
	v_cvt_pk_bf16_f32 v192, v192, v193
	v_cvt_pk_bf16_f32 v193, v212, v213
	v_cvt_pk_bf16_f32 v194, v194, v195
	v_cvt_pk_bf16_f32 v195, v208, v209
	v_mov_b32_e32 v234, v192
	v_mov_b32_e32 v235, v193
	v_mov_b32_e32 v236, v194
	v_mov_b32_e32 v237, v195
	v_pk_mul_f32 v[208:209], v[8:9], v[196:197] op_sel_hi:[1,0]
	v_pk_mul_f32 v[212:213], v[16:17], v[196:197] op_sel_hi:[1,0]
	v_pk_mul_f32 v[194:195], v[6:7], v[196:197] op_sel_hi:[1,0]
	v_pk_mul_f32 v[192:193], v[14:15], v[196:197] op_sel_hi:[1,0]
	s_nop 0
	v_cvt_pk_bf16_f32 v192, v192, v193
	v_cvt_pk_bf16_f32 v193, v212, v213
	v_cvt_pk_bf16_f32 v194, v194, v195
	v_cvt_pk_bf16_f32 v195, v208, v209
	v_mov_b32_e32 v238, v192
	v_mov_b32_e32 v239, v193
	v_mov_b32_e32 v240, v194
	v_mov_b32_e32 v241, v195
	s_nop 1
	v_permlane16_swap_b32_e32 v234, v238
	v_permlane16_swap_b32_e32 v235, v239
	v_permlane16_swap_b32_e32 v236, v240
	v_permlane16_swap_b32_e32 v237, v241
	v_permlane32_swap_b32_e32 v234, v238
	v_permlane32_swap_b32_e32 v235, v239
	v_permlane32_swap_b32_e32 v236, v240
	v_permlane32_swap_b32_e32 v237, v241
	v_lshl_add_u64 v[242:243], v[150:151], 0, v[244:245]
	global_store_dwordx4 v[242:243], v[234:237], off
	global_store_dwordx4 v[242:243], v[238:241], off offset:64
